# grid barrier: non-leader workgroups issue their L1 invalidate before waiting for the release (the workgroup is quiescent in between); on top of v138
# speedup vs baseline: 1.0201x; 1.0054x over previous
; __device__ __forceinline__ unsigned xb_ld(unsigned* p)              { return __hip_atomic_load(p, __ATOMIC_RELAXED, __HIP_MEMORY_SCOPE_AGENT); }
; __device__ __forceinline__ unsigned xb_add(unsigned* p, unsigned v) { return __hip_atomic_fetch_add(p, v, __ATOMIC_RELAXED, __HIP_MEMORY_SCOPE_AGENT); }
; #define XB_SPIN(cond, bar) do { unsigned _sp = 0; while (cond) { __builtin_amdgcn_s_sleep(1); \
;     if ((++_sp & 255u) == 0u) { if (xb_ld(&(bar)[XB_TMO])) break; if (_sp > XB_SPIN_CAP) { atomicAdd(&(bar)[XB_TMO], 1u); break; } } } } while (0)
; __device__ __forceinline__ void xcd_barrier(const XcdBarrier& b) {
;     ...
;         const unsigned old = xb_add(&bar[XB_XSUB(b.x)], 1u);
;         const unsigned gen = old / nloc;
;         if (old + 1u == (gen + 1u) * nloc) {
;             __builtin_amdgcn_fence(__ATOMIC_RELEASE, "agent");
;             asm volatile("s_waitcnt vmcnt(0)" ::: "memory");
;             const unsigned og = xb_add(&bar[XB_TOP], 1u);
;             const unsigned tg = og / nx;
;             if (og + 1u == (tg + 1u) * nx) xb_add(&bar[XB_TOPGEN], 1u);
;             else XB_SPIN(xb_ld(&bar[XB_TOPGEN]) == tg, bar);
;             __builtin_amdgcn_fence(__ATOMIC_ACQUIRE, "agent");
;             xb_add(&bar[XB_XGEN(b.x)], 1u);
;             asm volatile("s_waitcnt vmcnt(0)" ::: "memory");
;         } else {
;             XB_SPIN(xb_ld(&bar[XB_XGEN(b.x)]) == gen, bar);
;             __builtin_amdgcn_fence(__ATOMIC_ACQUIRE, "agent");
;             asm volatile("s_waitcnt vmcnt(0)" ::: "memory");
.LBB0_121:
	s_or_b64 exec, exec, s[6:7]
	v_cvt_f32_u32_e32 v4, v2
	s_waitcnt vmcnt(0)
	v_readfirstlane_b32 s4, v3
	v_sub_u32_e32 v3, 0, v2
	v_rcp_iflag_f32_e32 v4, v4
	v_add_u32_e32 v5, s4, v1
	v_mul_f32_e32 v4, 0x4f7ffffe, v4
	v_cvt_u32_f32_e32 v4, v4
	v_mul_lo_u32 v1, v3, v4
	v_mul_hi_u32 v1, v4, v1
	v_add_u32_e32 v1, v4, v1
	v_mul_hi_u32 v1, v5, v1
	v_mul_lo_u32 v3, v1, v2
	v_sub_u32_e32 v3, v5, v3
	v_add_u32_e32 v4, 1, v1
	v_cmp_ge_u32_e32 vcc, v3, v2
	s_nop 1
	v_cndmask_b32_e32 v1, v1, v4, vcc
	v_sub_u32_e32 v4, v3, v2
	v_cndmask_b32_e32 v3, v3, v4, vcc
	v_add_u32_e32 v4, 1, v1
	v_cmp_ge_u32_e32 vcc, v3, v2
	v_add_u32_e32 v3, 1, v5
	s_nop 0
	v_cndmask_b32_e32 v1, v1, v4, vcc
	v_mul_lo_u32 v4, v2, v1
	v_add_u32_e32 v2, v4, v2
	v_cmp_ne_u32_e32 vcc, v3, v2
	s_and_saveexec_b64 s[4:5], vcc
	s_xor_b64 s[4:5], exec, s[4:5]
	s_cbranch_execz .LBB0_135
	s_waitcnt lgkmcnt(0)
	buffer_inv sc1
	v_mov_b32_e32 v0, 0x2000
	global_load_dword v0, v0, s[2:3] offset:1024 sc1
	s_add_u32 s20, s2, 0x2400
	s_addc_u32 s21, s3, 0
	s_waitcnt vmcnt(0)
	v_cmp_eq_u32_e32 vcc, v0, v1
	s_and_saveexec_b64 s[6:7], vcc
	s_cbranch_execz .LBB0_134
	s_add_u32 s16, s74, 0x70d4200
	s_addc_u32 s17, s75, 0
	s_mov_b32 s15, 1
	s_mov_b64 s[22:23], 0
	v_mov_b32_e32 v0, 0
	s_branch .LBB0_125

; __device__ __forceinline__ unsigned xb_ld(unsigned* p)              { return __hip_atomic_load(p, __ATOMIC_RELAXED, __HIP_MEMORY_SCOPE_AGENT); }
; #define XB_SPIN(cond, bar) do { unsigned _sp = 0; while (cond) { __builtin_amdgcn_s_sleep(1); \
;     if ((++_sp & 255u) == 0u) { if (xb_ld(&(bar)[XB_TMO])) break; if (_sp > XB_SPIN_CAP) { atomicAdd(&(bar)[XB_TMO], 1u); break; } } } } while (0)
; __device__ __forceinline__ void xcd_barrier(const XcdBarrier& b) {
;     ...
;             XB_SPIN(xb_ld(&bar[XB_XGEN(b.x)]) == gen, bar);
;             __builtin_amdgcn_fence(__ATOMIC_ACQUIRE, "agent");
;             asm volatile("s_waitcnt vmcnt(0)" ::: "memory");
.LBB0_134:
	s_or_b64 exec, exec, s[6:7]
	s_waitcnt vmcnt(0)
	s_waitcnt vmcnt(0)

; __device__ __forceinline__ unsigned xb_ld(unsigned* p)              { return __hip_atomic_load(p, __ATOMIC_RELAXED, __HIP_MEMORY_SCOPE_AGENT); }
; __device__ __forceinline__ unsigned xb_add(unsigned* p, unsigned v) { return __hip_atomic_fetch_add(p, v, __ATOMIC_RELAXED, __HIP_MEMORY_SCOPE_AGENT); }
; #define XB_SPIN(cond, bar) do { unsigned _sp = 0; while (cond) { __builtin_amdgcn_s_sleep(1); \
;     if ((++_sp & 255u) == 0u) { if (xb_ld(&(bar)[XB_TMO])) break; if (_sp > XB_SPIN_CAP) { atomicAdd(&(bar)[XB_TMO], 1u); break; } } } } while (0)
; __device__ __forceinline__ void xcd_barrier(const XcdBarrier& b) {
;     ...
;         const unsigned old = xb_add(&bar[XB_XSUB(b.x)], 1u);
;         const unsigned gen = old / nloc;
;         if (old + 1u == (gen + 1u) * nloc) {
;             __builtin_amdgcn_fence(__ATOMIC_RELEASE, "agent");
;             asm volatile("s_waitcnt vmcnt(0)" ::: "memory");
;             const unsigned og = xb_add(&bar[XB_TOP], 1u);
;             const unsigned tg = og / nx;
;             if (og + 1u == (tg + 1u) * nx) xb_add(&bar[XB_TOPGEN], 1u);
;             else XB_SPIN(xb_ld(&bar[XB_TOPGEN]) == tg, bar);
;             __builtin_amdgcn_fence(__ATOMIC_ACQUIRE, "agent");
;             xb_add(&bar[XB_XGEN(b.x)], 1u);
;             asm volatile("s_waitcnt vmcnt(0)" ::: "memory");
;         } else {
;             XB_SPIN(xb_ld(&bar[XB_XGEN(b.x)]) == gen, bar);
;             __builtin_amdgcn_fence(__ATOMIC_ACQUIRE, "agent");
;             asm volatile("s_waitcnt vmcnt(0)" ::: "memory");
.LBB0_335:
	s_or_b64 exec, exec, s[6:7]
	v_cvt_f32_u32_e32 v4, v2
	s_waitcnt vmcnt(0)
	v_readfirstlane_b32 s4, v3
	v_sub_u32_e32 v3, 0, v2
	v_rcp_iflag_f32_e32 v4, v4
	v_add_u32_e32 v5, s4, v1
	v_mul_f32_e32 v4, 0x4f7ffffe, v4
	v_cvt_u32_f32_e32 v4, v4
	v_mul_lo_u32 v1, v3, v4
	v_mul_hi_u32 v1, v4, v1
	v_add_u32_e32 v1, v4, v1
	v_mul_hi_u32 v1, v5, v1
	v_mul_lo_u32 v3, v1, v2
	v_sub_u32_e32 v3, v5, v3
	v_add_u32_e32 v4, 1, v1
	v_cmp_ge_u32_e32 vcc, v3, v2
	s_nop 1
	v_cndmask_b32_e32 v1, v1, v4, vcc
	v_sub_u32_e32 v4, v3, v2
	v_cndmask_b32_e32 v3, v3, v4, vcc
	v_add_u32_e32 v4, 1, v1
	v_cmp_ge_u32_e32 vcc, v3, v2
	v_add_u32_e32 v3, 1, v5
	s_nop 0
	v_cndmask_b32_e32 v1, v1, v4, vcc
	v_mul_lo_u32 v4, v2, v1
	v_add_u32_e32 v2, v4, v2
	v_cmp_ne_u32_e32 vcc, v3, v2
	s_and_saveexec_b64 s[4:5], vcc
	s_xor_b64 s[4:5], exec, s[4:5]
	s_cbranch_execz .LBB0_349
	s_waitcnt lgkmcnt(0)
	buffer_inv sc1
	v_mov_b32_e32 v0, 0x2000
	global_load_dword v0, v0, s[2:3] offset:1024 sc1
	s_add_u32 s10, s2, 0x2400
	s_addc_u32 s11, s3, 0
	s_waitcnt vmcnt(0)
	v_cmp_eq_u32_e32 vcc, v0, v1
	s_and_saveexec_b64 s[6:7], vcc
	s_cbranch_execz .LBB0_348
	s_add_u32 s8, s74, 0x70d4200
	s_addc_u32 s9, s75, 0
	s_mov_b32 s15, 1
	s_mov_b64 s[16:17], 0
	v_mov_b32_e32 v0, 0
	s_branch .LBB0_339

; __device__ __forceinline__ unsigned xb_ld(unsigned* p)              { return __hip_atomic_load(p, __ATOMIC_RELAXED, __HIP_MEMORY_SCOPE_AGENT); }
; __device__ __forceinline__ unsigned xb_add(unsigned* p, unsigned v) { return __hip_atomic_fetch_add(p, v, __ATOMIC_RELAXED, __HIP_MEMORY_SCOPE_AGENT); }
; #define XB_SPIN(cond, bar) do { unsigned _sp = 0; while (cond) { __builtin_amdgcn_s_sleep(1); \
;     if ((++_sp & 255u) == 0u) { if (xb_ld(&(bar)[XB_TMO])) break; if (_sp > XB_SPIN_CAP) { atomicAdd(&(bar)[XB_TMO], 1u); break; } } } } while (0)
; __device__ __forceinline__ void xcd_barrier(const XcdBarrier& b) {
;     ...
;         const unsigned old = xb_add(&bar[XB_XSUB(b.x)], 1u);
;         const unsigned gen = old / nloc;
;         if (old + 1u == (gen + 1u) * nloc) {
;             __builtin_amdgcn_fence(__ATOMIC_RELEASE, "agent");
;             asm volatile("s_waitcnt vmcnt(0)" ::: "memory");
;             const unsigned og = xb_add(&bar[XB_TOP], 1u);
;             const unsigned tg = og / nx;
;             if (og + 1u == (tg + 1u) * nx) xb_add(&bar[XB_TOPGEN], 1u);
;             else XB_SPIN(xb_ld(&bar[XB_TOPGEN]) == tg, bar);
;             __builtin_amdgcn_fence(__ATOMIC_ACQUIRE, "agent");
;             xb_add(&bar[XB_XGEN(b.x)], 1u);
;             asm volatile("s_waitcnt vmcnt(0)" ::: "memory");
;         } else {
;             XB_SPIN(xb_ld(&bar[XB_XGEN(b.x)]) == gen, bar);
;             __builtin_amdgcn_fence(__ATOMIC_ACQUIRE, "agent");
;             asm volatile("s_waitcnt vmcnt(0)" ::: "memory");
.LBB0_1034:
	s_or_b64 exec, exec, s[6:7]
	v_cvt_f32_u32_e32 v4, v2
	s_waitcnt vmcnt(0)
	v_readfirstlane_b32 s4, v3
	v_sub_u32_e32 v3, 0, v2
	v_rcp_iflag_f32_e32 v4, v4
	v_add_u32_e32 v5, s4, v1
	v_mul_f32_e32 v4, 0x4f7ffffe, v4
	v_cvt_u32_f32_e32 v4, v4
	v_mul_lo_u32 v1, v3, v4
	v_mul_hi_u32 v1, v4, v1
	v_add_u32_e32 v1, v4, v1
	v_mul_hi_u32 v1, v5, v1
	v_mul_lo_u32 v3, v1, v2
	v_sub_u32_e32 v3, v5, v3
	v_add_u32_e32 v4, 1, v1
	v_cmp_ge_u32_e32 vcc, v3, v2
	s_nop 1
	v_cndmask_b32_e32 v1, v1, v4, vcc
	v_sub_u32_e32 v4, v3, v2
	v_cndmask_b32_e32 v3, v3, v4, vcc
	v_add_u32_e32 v4, 1, v1
	v_cmp_ge_u32_e32 vcc, v3, v2
	v_add_u32_e32 v3, 1, v5
	s_nop 0
	v_cndmask_b32_e32 v1, v1, v4, vcc
	v_mul_lo_u32 v4, v2, v1
	v_add_u32_e32 v2, v4, v2
	v_cmp_ne_u32_e32 vcc, v3, v2
	s_and_saveexec_b64 s[4:5], vcc
	s_xor_b64 s[4:5], exec, s[4:5]
	s_cbranch_execz .LBB0_1048
	s_waitcnt lgkmcnt(0)
	buffer_inv sc1
	v_mov_b32_e32 v0, 0x2000
	global_load_dword v0, v0, s[2:3] offset:1024 sc1
	s_add_u32 s10, s2, 0x2400
	s_addc_u32 s11, s3, 0
	s_waitcnt vmcnt(0)
	v_cmp_eq_u32_e32 vcc, v0, v1
	s_and_saveexec_b64 s[6:7], vcc
	s_cbranch_execz .LBB0_1047
	s_add_u32 s8, s74, 0x70d4200
	s_addc_u32 s9, s75, 0
	s_mov_b32 s15, 1
	s_mov_b64 s[12:13], 0
	v_mov_b32_e32 v0, 0
	s_branch .LBB0_1038
